# DeltaNet prep next-unit prefetch: row addresses from scalar bases (global_load with SGPR base + per-lane offset, s_add per row) and wave-uniform edge handling instead of 22 per-load 64-bit VALU addres
# speedup vs baseline: 1.0131x; 1.0103x over previous
.LBB0_569:
	s_andn2_b64 vcc, exec, s[8:9]
	s_cbranch_vccnz .LBB0_600
	s_bfe_u32 s12, s2, 0x30006
	s_ashr_i32 s8, s2, 9
	s_add_i32 s61, s51, s61
	s_lshl_b32 s15, s12, 7
	s_and_b32 s10, s61, 0xfc0
	s_ashr_i32 s9, s8, 31
	s_lshl_b64 s[8:9], s[8:9], 12
	s_or_b32 s8, s8, s10
	s_mul_i32 s14, s9, 0x2200
	v_add3_u32 v0, v42, v13, s15
	v_readfirstlane_b32 s13, v10
	v_add_u32_e32 v2, 0x400, v0
	v_lshrrev_b32_e32 v3, 5, v81
	v_mul_u32_u24_e32 v3, 0x11000, v3
	v_lshl_add_u32 v2, v2, 1, v3
	v_or_b32_e32 v4, s15, v11
	v_lshlrev_b32_e32 v4, 1, v4
	s_and_b32 s45, s13, 24
	s_lshl_b32 s16, s45, 1
	s_add_i32 s16, s16, s8
	s_add_i32 s16, s16, -3
	s_mul_i32 s16, s16, 0x2200
	s_ashr_i32 s17, s16, 31
	s_add_u32 s16, s24, s16
	s_addc_u32 s17, s25, s17
	s_or_b32 s45, s45, s10
	s_cmp_eq_u32 s45, 0
	s_cbranch_scc1 .Lpf_pedge
	global_load_dwordx2 v[20:21], v2, s[16:17]
	s_add_u32 s16, s16, 0x2200
	s_addc_u32 s17, s17, 0
	global_load_dwordx2 v[18:19], v2, s[16:17]
	s_add_u32 s16, s16, 0x2200
	s_addc_u32 s17, s17, 0
	global_load_dwordx2 v[22:23], v2, s[16:17]
	s_add_u32 s16, s16, 0x2200
	s_addc_u32 s17, s17, 0
	s_branch .Lpf_pmain
.Lpf_pedge:
	v_mov_b32_e32 v20, 0
	v_mov_b32_e32 v21, 0
	v_mov_b32_e32 v18, 0
	v_mov_b32_e32 v19, 0
	v_mov_b32_e32 v22, 0
	v_mov_b32_e32 v23, 0
	s_mov_b64 s[46:47], exec
	s_mov_b32 exec_lo, 0
	global_load_dwordx2 v[20:21], v2, s[16:17]
	s_add_u32 s16, s16, 0x2200
	s_addc_u32 s17, s17, 0
	global_load_dwordx2 v[18:19], v2, s[16:17]
	s_add_u32 s16, s16, 0x2200
	s_addc_u32 s17, s17, 0
	global_load_dwordx2 v[22:23], v2, s[16:17]
	s_add_u32 s16, s16, 0x2200
	s_addc_u32 s17, s17, 0
	s_mov_b64 exec, s[46:47]
.Lpf_pmain:
	global_load_dwordx2 v[24:25], v2, s[16:17]
	s_add_u32 s16, s16, 0x2200
	s_addc_u32 s17, s17, 0
	global_load_dwordx2 v[26:27], v2, s[16:17]
	s_add_u32 s16, s16, 0x2200
	s_addc_u32 s17, s17, 0
	global_load_dwordx2 v[28:29], v2, s[16:17]
	s_add_u32 s16, s16, 0x2200
	s_addc_u32 s17, s17, 0
	global_load_dwordx2 v[30:31], v2, s[16:17]
	s_add_u32 s16, s16, 0x2200
	s_addc_u32 s17, s17, 0
	global_load_dwordx2 v[32:33], v2, s[16:17]
	s_add_u32 s16, s16, 0x2200
	s_addc_u32 s17, s17, 0
	global_load_dwordx2 v[34:35], v2, s[16:17]
	s_add_u32 s16, s16, 0x2200
	s_addc_u32 s17, s17, 0
	global_load_dwordx2 v[36:37], v2, s[16:17]
	s_add_u32 s16, s16, 0x2200
	s_addc_u32 s17, s17, 0
	global_load_dwordx2 v[38:39], v2, s[16:17]
	s_add_i32 s16, s13, s8
	s_add_i32 s16, s16, -3
	s_mul_i32 s16, s16, 0x2200
	s_ashr_i32 s17, s16, 31
	s_add_u32 s16, s24, s16
	s_addc_u32 s17, s25, s17
	s_or_b32 s45, s13, s10
	s_cmp_eq_u32 s45, 0
	s_cbranch_scc1 .Lpf_qedge
	global_load_dword v70, v4, s[16:17]
	s_add_u32 s16, s16, 0x2200
	s_addc_u32 s17, s17, 0
	global_load_dword v69, v4, s[16:17]
	s_add_u32 s16, s16, 0x2200
	s_addc_u32 s17, s17, 0
	global_load_dword v72, v4, s[16:17]
	s_add_u32 s16, s16, 0x2200
	s_addc_u32 s17, s17, 0
	s_branch .Lpf_qmain
.Lpf_qedge:
	v_mov_b32_e32 v70, 0
	v_mov_b32_e32 v69, 0
	v_mov_b32_e32 v72, 0
	s_add_u32 s16, s16, 0x6600
	s_addc_u32 s17, s17, 0
.Lpf_qmain:
	global_load_dword v71, v4, s[16:17]
	s_add_u32 s16, s16, 0x2200
	s_addc_u32 s17, s17, 0
	global_load_dword v74, v4, s[16:17]
	s_add_u32 s16, s16, 0x2200
	s_addc_u32 s17, s17, 0
	global_load_dword v73, v4, s[16:17]
	s_add_u32 s16, s16, 0x2200
	s_addc_u32 s17, s17, 0
	global_load_dword v76, v4, s[16:17]
	s_add_u32 s16, s16, 0x2200
	s_addc_u32 s17, s17, 0
	global_load_dword v75, v4, s[16:17]
	s_add_u32 s16, s16, 0x2200
	s_addc_u32 s17, s17, 0
	global_load_dword v78, v4, s[16:17]
	s_add_u32 s16, s16, 0x2200
	s_addc_u32 s17, s17, 0
	global_load_dword v77, v4, s[16:17]
	s_add_u32 s16, s16, 0x2200
	s_addc_u32 s17, s17, 0
	global_load_dword v79, v4, s[16:17]
	s_and_saveexec_b64 s[10:11], s[6:7]
	s_cbranch_execz .LBB0_522
	v_or_b32_e32 v0, s8, v81
	v_mov_b64_e32 v[2:3], s[24:25]
	v_mad_u64_u32 v[2:3], s[6:7], v0, s87, v[2:3]
	v_add_u32_e32 v3, s14, v3
	s_lshl_b32 s62, s12, 1
	v_lshl_add_u64 v[2:3], v[2:3], 0, s[62:63]
	v_add_co_u32_e32 v2, vcc, 0x2000, v2
	s_nop 1
	v_addc_co_u32_e32 v3, vcc, 0, v3, vcc
	global_load_ushort v41, v[2:3], off
	s_nop 0
	global_load_ushort v40, v[2:3], off offset:16
	s_branch .LBB0_522
